# v61 + prep phase: depthwise conv weights staged in LDS per block, per-row weight loads are ds_read_b128
# speedup vs baseline: 1.1312x; 1.0059x over previous
.LBB0_565:
	s_andn2_b64 vcc, exec, s[36:37]
	s_cbranch_vccnz .LBB0_613
	s_waitcnt vmcnt(0)
	v_mov_b32_e32 v4, v168
	v_mov_b32_e32 v0, v168
	v_readlane_b32 s0, v254, 7
	v_ashrrev_i32_e32 v0, 6, v0
	s_movk_i32 s2, 0x3800
	v_add_u32_e32 v0, s0, v0
	v_readlane_b32 s0, v254, 46
	v_cmp_gt_i32_e32 vcc, s2, v0
	v_readlane_b32 s1, v254, 47
	s_and_saveexec_b64 s[60:61], vcc
	s_cbranch_execz .LBB0_612
	v_readlane_b32 s0, v254, 61
	v_readlane_b32 s80, v250, 17
	v_and_b32_e32 v1, 63, v4
	v_readlane_b32 s1, v254, 62
	s_mul_i32 s20, s0, 0x4800
	v_readlane_b32 s90, v250, 27
	v_lshlrev_b32_e32 v72, 3, v1
	s_mul_i32 s2, s0, 0x180
	s_mul_hi_i32 s3, s0, 0x4800
	v_readlane_b32 s91, v250, 28
	s_add_u32 s52, s90, s20
	v_and_b32_e32 v74, 56, v72
	v_and_b32_e32 v5, 0xf8, v72
	v_readlane_b32 s1, v254, 63
	s_addc_u32 s53, s91, s3
	v_bfe_u32 v3, v4, 3, 3
	s_waitcnt lgkmcnt(0)
	v_or_b32_e32 v6, s1, v74
	v_and_b32_e32 v12, 2, v4
	v_and_b32_e32 v13, 1, v4
	v_add_u32_e32 v8, s2, v72
	v_lshl_or_b32 v10, s0, 8, v5
	v_readlane_b32 s0, v250, 1
	v_cmp_eq_u32_e64 s[48:49], 0, v12
	v_cmp_eq_u32_e64 s[50:51], 0, v13
	v_lshlrev_b32_e32 v12, 8, v3
	v_mov_b32_e32 v13, v2
	v_readlane_b32 s2, v250, 3
	v_readlane_b32 s3, v250, 4
	v_readlane_b32 s4, v250, 5
	v_readlane_b32 s5, v250, 6
	v_lshlrev_b32_e32 v16, 2, v74
	v_mov_b32_e32 v17, v2
	v_lshl_add_u64 v[14:15], s[4:5], 0, v[12:13]
	v_readlane_b32 s2, v252, 59
	v_lshl_add_u64 v[78:79], v[14:15], 0, v[16:17]
	v_lshlrev_b32_e32 v14, 1, v74
	v_mov_b32_e32 v15, v2
	v_readlane_b32 s3, v252, 60
	v_readlane_b32 s6, v250, 7
	v_readlane_b32 s7, v250, 8
	v_lshl_add_u64 v[86:87], s[2:3], 0, v[14:15]
	v_readlane_b32 s2, v253, 44
	v_lshl_add_u64 v[12:13], s[6:7], 0, v[12:13]
	v_lshlrev_b32_e32 v14, 4, v1
	v_readlane_b32 s3, v253, 45
	v_readlane_b32 s8, v250, 9
	v_readlane_b32 s9, v250, 10
	v_readlane_b32 s10, v250, 11
	v_readlane_b32 s11, v250, 12
	v_readlane_b32 s12, v250, 13
	v_readlane_b32 s13, v250, 14
	v_readlane_b32 s14, v250, 15
	v_readlane_b32 s15, v250, 16
	v_lshl_add_u64 v[80:81], v[12:13], 0, v[16:17]
	v_lshlrev_b32_e32 v12, 5, v1
	v_mov_b32_e32 v13, v2
	v_lshl_add_u64 v[88:89], s[2:3], 0, v[14:15]
	v_readlane_b32 s2, v252, 49
	v_ashrrev_i32_e32 v7, 31, v6
	v_lshl_add_u64 v[82:83], s[8:9], 0, v[12:13]
	v_lshl_add_u64 v[84:85], s[10:11], 0, v[12:13]
	v_readlane_b32 s4, v254, 30
	v_readlane_b32 s3, v252, 50
	v_readlane_b32 s81, v250, 18
	v_bfe_u32 v73, v4, 3, 1
	v_readlane_b32 s18, v254, 44
	v_readlane_b32 s19, v254, 45
	v_lshl_add_u64 v[90:91], s[2:3], 0, v[14:15]
	v_lshlrev_b64 v[6:7], 2, v[6:7]
	v_readlane_b32 s2, v253, 24
	v_lshl_add_u64 v[92:93], s[18:19], 0, v[6:7]
	v_lshl_add_u64 v[94:95], s[80:81], 0, v[6:7]
	v_lshlrev_b32_e32 v6, 8, v73
	v_mov_b32_e32 v7, v2
	v_readlane_b32 s3, v253, 25
	v_lshl_add_u64 v[104:105], s[52:53], 0, v[12:13]
	s_mov_b64 s[20:21], 0x1800
	v_lshl_add_u64 v[18:19], s[2:3], 0, v[6:7]
	v_readlane_b32 s2, v253, 26
	v_readlane_b32 s3, v253, 27
	v_lshl_add_u64 v[106:107], v[104:105], 0, s[20:21]
	s_mov_b64 s[20:21], 0x3800
	v_lshl_add_u64 v[6:7], s[2:3], 0, v[6:7]
	s_mov_b64 s[2:3], 0x3000
	v_lshl_add_u64 v[108:109], v[104:105], 0, s[2:3]
	s_mov_b64 s[2:3], 0x2000
	v_lshl_add_u64 v[110:111], v[104:105], 0, s[2:3]
	s_mov_b64 s[2:3], 0x1000
	v_lshl_add_u64 v[114:115], v[104:105], 0, s[2:3]
	s_mov_b64 s[2:3], 0x2800
	v_lshl_add_u64 v[116:117], v[104:105], 0, s[2:3]
	s_mov_b64 s[2:3], 0x4000
	v_lshl_add_u64 v[118:119], v[104:105], 0, s[2:3]
	s_movk_i32 s2, 0x300
	v_lshl_add_u64 v[98:99], v[6:7], 0, v[16:17]
	v_lshl_add_u64 v[112:113], v[104:105], 0, s[20:21]
	v_mad_i64_i32 v[6:7], s[20:21], v0, s2, v[14:15]
	s_mov_b64 s[20:21], 0x6c50000
	s_movk_i32 s2, 0x1740
	v_and_b32_e32 v20, 15, v4
	v_and_b32_e32 v22, 3, v4
	v_lshl_add_u64 v[120:121], v[6:7], 0, s[20:21]
	v_mad_i64_i32 v[6:7], s[20:21], v0, s2, 0
	v_and_b32_e32 v4, 31, v4
	v_lshl_or_b32 v6, v22, 4, v6
	s_mov_b64 s[20:21], 0x1390b00
	v_lshlrev_b32_e32 v4, 4, v4
	v_mov_b32_e32 v5, v2
	v_cmp_gt_u32_e64 s[42:43], 48, v1
	v_lshl_add_u64 v[124:125], v[6:7], 0, s[20:21]
	v_mad_i64_i32 v[4:5], s[20:21], v0, s2, v[4:5]
	v_cndmask_b32_e64 v21, 0, v72, s[42:43]
	s_mov_b64 s[20:21], 0x1390900
	v_lshl_add_u64 v[126:127], v[4:5], 0, s[20:21]
	v_lshlrev_b32_e32 v4, 1, v21
	v_mov_b32_e32 v5, v2
	v_mad_i64_i32 v[4:5], s[20:21], v0, s2, v[4:5]
	v_cmp_gt_u32_e64 s[36:37], 16, v1
	v_cmp_gt_u32_e64 s[38:39], 32, v1
	v_cmp_gt_u32_e64 s[40:41], 4, v1
	v_readlane_b32 s1, v250, 2
	v_ashrrev_i32_e32 v1, 31, v0
	s_mov_b64 s[20:21], 0x1390600
	v_readlane_b32 s82, v250, 19
	v_readlane_b32 s83, v250, 20
	v_readlane_b32 s84, v250, 21
	v_readlane_b32 s85, v250, 22
	v_and_b32_e32 v23, 8, v72
	v_ashrrev_i32_e32 v9, 31, v8
	v_ashrrev_i32_e32 v11, 31, v10
	v_readlane_b32 s0, v254, 46
	v_lshlrev_b64 v[122:123], 10, v[0:1]
	v_lshl_add_u64 v[128:129], v[4:5], 0, s[20:21]
	v_lshlrev_b32_e32 v4, 4, v20
	v_mov_b32_e32 v5, v2
	v_cmp_gt_u32_e64 s[44:45], 32, v74
	v_lshlrev_b32_e32 v76, 9, v74
	v_mov_b32_e32 v77, v2
	v_cmp_lt_u32_e64 s[46:47], 1, v22
	v_readlane_b32 s1, v254, 47
	v_readlane_b32 s5, v254, 31
	v_readlane_b32 s6, v254, 32
	v_readlane_b32 s7, v254, 33
	v_readlane_b32 s8, v254, 34
	v_readlane_b32 s9, v254, 35
	v_readlane_b32 s10, v254, 36
	v_readlane_b32 s11, v254, 37
	v_readlane_b32 s12, v254, 38
	v_readlane_b32 s13, v254, 39
	v_readlane_b32 s14, v254, 40
	v_readlane_b32 s15, v254, 41
	v_readlane_b32 s16, v254, 42
	v_readlane_b32 s17, v254, 43
	v_lshl_add_u64 v[96:97], v[18:19], 0, v[16:17]
	v_lshl_add_u64 v[100:101], v[8:9], 2, s[82:83]
	v_lshl_add_u64 v[102:103], v[10:11], 2, s[84:85]
	v_or_b32_e32 v122, v122, v14
	v_mad_i64_i32 v[130:131], s[20:21], v0, s2, v[4:5]
	v_mad_i64_i32 v[132:133], s[20:21], v0, s2, v[14:15]
	s_mov_b64 s[62:63], 0
	v_lshlrev_b32_e32 v75, 2, v23
	v_readlane_b32 s86, v250, 23
	v_readlane_b32 s87, v250, 24
	v_readlane_b32 s88, v250, 25
	v_readlane_b32 s89, v250, 26
	v_readlane_b32 s92, v250, 29
	v_readlane_b32 s93, v250, 30
	v_readlane_b32 s94, v250, 31
	v_readlane_b32 s95, v250, 32
	v_and_b32_e32 v162, 63, v168
	v_lshlrev_b32_e32 v162, 5, v162
	v_lshlrev_b32_e32 v163, 4, v168
	v_add_u32_e32 v164, 0x1000, v163
	v_add_u32_e32 v165, 0x2000, v163
	v_add_u32_e32 v166, 0x3000, v163
	v_add_u32_e32 v167, 0x4000, v163
	v_min_u32_e32 v167, 0x47f0, v167
	global_load_dwordx4 v[202:205], v163, s[52:53]
	global_load_dwordx4 v[206:209], v164, s[52:53]
	global_load_dwordx4 v[210:213], v165, s[52:53]
	global_load_dwordx4 v[214:217], v166, s[52:53]
	global_load_dwordx4 v[218:221], v167, s[52:53]
	s_waitcnt vmcnt(0)
	ds_write_b128 v163, v[202:205]
	ds_write_b128 v164, v[206:209]
	ds_write_b128 v165, v[210:213]
	ds_write_b128 v166, v[214:217]
	ds_write_b128 v167, v[218:221]
	s_waitcnt lgkmcnt(0)
	s_barrier
	s_branch .LBB0_570
.LBB0_568:
	s_or_b64 exec, exec, s[54:55]
	s_waitcnt lgkmcnt(2)
	ds_read_b128 v[52:55], v162 offset:16
	ds_read_b128 v[40:43], v162
	s_waitcnt lgkmcnt(0)
	ds_read_b128 v[56:59], v162 offset:6160
	ds_read_b128 v[60:63], v162 offset:6144
	v_lshlrev_b32_e32 v46, 16, v31
	v_and_b32_e32 v47, 0xffff0000, v31
	v_lshlrev_b32_e32 v44, 16, v39
	v_and_b32_e32 v45, 0xffff0000, v39
	v_lshlrev_b32_e32 v50, 16, v35
	v_and_b32_e32 v51, 0xffff0000, v35
	v_and_b32_e32 v39, 0xffff0000, v30
	s_mov_b32 s2, 0x7d30000
	s_waitcnt lgkmcnt(0)
	v_pk_mul_f32 v[46:47], v[58:59], v[46:47]
	s_nop 0
	v_pk_fma_f32 v[48:49], v[54:55], v[44:45], v[46:47]
	ds_read_b128 v[64:67], v162 offset:12304
	ds_read_b128 v[44:47], v162 offset:12288
	v_lshlrev_b32_e32 v54, 16, v38
	v_and_b32_e32 v55, 0xffff0000, v38
	v_lshlrev_b32_e32 v38, 16, v30
	s_waitcnt lgkmcnt(0)
	v_pk_fma_f32 v[48:49], v[66:67], v[50:51], v[48:49]
	s_nop 0
	v_mul_f32_e32 v31, 0xbfb8aa3b, v48
	v_exp_f32_e32 v31, v31
	s_nop 0
	v_add_f32_e32 v31, 1.0, v31
	v_rcp_f32_e32 v50, v31
	v_mul_f32_e32 v31, 0xbfb8aa3b, v49
	v_exp_f32_e32 v31, v31
	s_nop 0
	v_add_f32_e32 v31, 1.0, v31
	v_rcp_f32_e32 v51, v31
	v_pk_mul_f32 v[30:31], v[56:57], v[38:39]
	v_lshlrev_b32_e32 v38, 16, v34
	v_pk_fma_f32 v[30:31], v[52:53], v[54:55], v[30:31]
	v_and_b32_e32 v39, 0xffff0000, v34
	v_lshlrev_b32_e32 v52, 16, v29
	v_and_b32_e32 v53, 0xffff0000, v29
	v_pk_fma_f32 v[30:31], v[64:65], v[38:39], v[30:31]
	v_lshlrev_b32_e32 v38, 16, v37
	v_and_b32_e32 v39, 0xffff0000, v37
	v_pk_mul_f32 v[52:53], v[62:63], v[52:53]
	v_and_b32_e32 v37, 0xffff0000, v28
	v_pk_fma_f32 v[38:39], v[42:43], v[38:39], v[52:53]
	v_lshlrev_b32_e32 v42, 16, v33
	v_and_b32_e32 v43, 0xffff0000, v33
	s_waitcnt lgkmcnt(0)
	v_pk_fma_f32 v[38:39], v[46:47], v[42:43], v[38:39]
	v_lshlrev_b32_e32 v46, 16, v36
	v_mul_f32_e32 v29, 0xbfb8aa3b, v38
	v_exp_f32_e32 v29, v29
	v_and_b32_e32 v47, 0xffff0000, v36
	v_lshlrev_b32_e32 v36, 16, v28
	v_mul_f32_e32 v34, 0xbfb8aa3b, v30
	v_add_f32_e32 v29, 1.0, v29
	v_rcp_f32_e32 v42, v29
	v_mul_f32_e32 v29, 0xbfb8aa3b, v39
	v_exp_f32_e32 v29, v29
	v_mul_f32_e32 v35, 0xbfb8aa3b, v31
	v_exp_f32_e32 v34, v34
	v_exp_f32_e32 v35, v35
	v_add_f32_e32 v29, 1.0, v29
	v_rcp_f32_e32 v43, v29
	v_pk_mul_f32 v[28:29], v[60:61], v[36:37]
	v_lshlrev_b32_e32 v36, 16, v32
	v_pk_fma_f32 v[28:29], v[40:41], v[46:47], v[28:29]
	v_and_b32_e32 v37, 0xffff0000, v32
	v_pk_fma_f32 v[28:29], v[44:45], v[36:37], v[28:29]
	v_add_f32_e32 v34, 1.0, v34
	v_mul_f32_e32 v32, 0xbfb8aa3b, v28
	v_mul_f32_e32 v33, 0xbfb8aa3b, v29
	v_exp_f32_e32 v32, v32
	v_exp_f32_e32 v33, v33
	v_add_f32_e32 v35, 1.0, v35
	v_rcp_f32_e32 v34, v34
	v_add_f32_e32 v32, 1.0, v32
	v_add_f32_e32 v33, 1.0, v33
	v_rcp_f32_e32 v32, v32
	v_rcp_f32_e32 v33, v33
	v_rcp_f32_e32 v35, v35
	v_pk_mul_f32 v[38:39], v[38:39], v[42:43]
	v_pk_mul_f32 v[48:49], v[48:49], v[50:51]
	v_pk_mul_f32 v[28:29], v[28:29], v[32:33]
	v_pk_mul_f32 v[42:43], v[38:39], v[38:39]
	v_pk_mul_f32 v[32:33], v[28:29], v[28:29]
	v_pk_mul_f32 v[30:31], v[30:31], v[34:35]
	v_add_f32_e32 v32, v32, v33
	v_add_f32_e32 v32, v32, v42
	v_pk_mul_f32 v[34:35], v[30:31], v[30:31]
	v_add_f32_e32 v32, v32, v43
	v_add_f32_e32 v32, v32, v34
	v_pk_mul_f32 v[50:51], v[48:49], v[48:49]
	v_add_f32_e32 v32, v32, v35
	v_add_f32_e32 v32, v32, v50
	v_add_f32_e32 v32, v32, v51
	ds_bpermute_b32 v33, v140, v32
	s_waitcnt lgkmcnt(0)
	v_add_f32_e32 v32, v32, v33
	ds_bpermute_b32 v33, v141, v32
	s_waitcnt lgkmcnt(0)
	v_add_f32_e32 v32, v32, v33
	ds_bpermute_b32 v33, v142, v32
	s_waitcnt lgkmcnt(0)
	v_add_f32_e32 v32, v32, v33
	v_add_f32_e32 v32, 0x358637bd, v32
	v_rsq_f32_e32 v32, v32
	s_nop 0
	v_mul_f32_e32 v32, 0x3e000000, v32
	v_pk_mul_f32 v[28:29], v[28:29], v[32:33] op_sel_hi:[1,0]
	v_pk_mul_f32 v[34:35], v[38:39], v[32:33] op_sel_hi:[1,0]
	v_pk_mul_f32 v[30:31], v[30:31], v[32:33] op_sel_hi:[1,0]
	v_pk_mul_f32 v[32:33], v[48:49], v[32:33] op_sel_hi:[1,0]
	v_cvt_pk_bf16_f32 v30, v30, v31
	v_cvt_pk_bf16_f32 v31, v32, v33
	v_add_co_u32_e32 v32, vcc, s2, v134
	v_cvt_pk_bf16_f32 v28, v28, v29
	v_cvt_pk_bf16_f32 v29, v34, v35
	v_addc_co_u32_e32 v33, vcc, 0, v135, vcc
	global_store_dwordx4 v[32:33], v[28:31], off
	s_nop 1
	ds_read_b128 v[40:43], v162 offset:2064
	s_nop 0
	ds_read_b128 v[28:31], v162 offset:2048
	ds_read_b128 v[44:47], v162 offset:8208
	ds_read_b128 v[48:51], v162 offset:8192
	v_lshlrev_b32_e32 v34, 16, v23
	v_and_b32_e32 v35, 0xffff0000, v23
	v_lshlrev_b32_e32 v32, 16, v27
	v_and_b32_e32 v33, 0xffff0000, v27
	v_lshlrev_b32_e32 v38, 16, v19
	v_and_b32_e32 v39, 0xffff0000, v19
	v_and_b32_e32 v27, 0xffff0000, v22
	s_mov_b32 s2, 0x8930000
	s_waitcnt lgkmcnt(0)
	v_pk_mul_f32 v[34:35], v[46:47], v[34:35]
	s_nop 0
	v_pk_fma_f32 v[36:37], v[42:43], v[32:33], v[34:35]
	ds_read_b128 v[52:55], v162 offset:14352
	ds_read_b128 v[32:35], v162 offset:14336
	v_lshlrev_b32_e32 v42, 16, v26
	v_and_b32_e32 v43, 0xffff0000, v26
	v_lshlrev_b32_e32 v26, 16, v22
	v_pk_mul_f32 v[22:23], v[44:45], v[26:27]
	v_lshlrev_b32_e32 v26, 16, v18
	v_pk_fma_f32 v[22:23], v[40:41], v[42:43], v[22:23]
	v_and_b32_e32 v27, 0xffff0000, v18
	v_lshlrev_b32_e32 v40, 16, v21
	v_and_b32_e32 v41, 0xffff0000, v21
	s_waitcnt lgkmcnt(0)
	v_pk_mul_f32 v[40:41], v[50:51], v[40:41]
	v_lshlrev_b32_e32 v42, 16, v8
	v_and_b32_e32 v43, 0xffff0000, v8
	v_lshlrev_b32_e32 v8, 16, v9
	v_and_b32_e32 v9, 0xffff0000, v9
	s_waitcnt lgkmcnt(0)
	v_pk_fma_f32 v[36:37], v[54:55], v[38:39], v[36:37]
	s_nop 0
	v_mul_f32_e32 v19, 0xbfb8aa3b, v36
	v_exp_f32_e32 v19, v19
	s_nop 0
	v_add_f32_e32 v19, 1.0, v19
	v_rcp_f32_e32 v38, v19
	v_mul_f32_e32 v19, 0xbfb8aa3b, v37
	v_exp_f32_e32 v19, v19
	s_nop 0
	v_add_f32_e32 v19, 1.0, v19
	v_rcp_f32_e32 v39, v19
	v_pk_fma_f32 v[18:19], v[52:53], v[26:27], v[22:23]
	v_lshlrev_b32_e32 v26, 16, v25
	v_and_b32_e32 v27, 0xffff0000, v25
	v_pk_fma_f32 v[26:27], v[30:31], v[26:27], v[40:41]
	v_lshlrev_b32_e32 v30, 16, v17
	v_and_b32_e32 v31, 0xffff0000, v17
	s_waitcnt lgkmcnt(0)
	v_pk_fma_f32 v[26:27], v[34:35], v[30:31], v[26:27]
	v_lshlrev_b32_e32 v34, 16, v24
	v_mul_f32_e32 v17, 0xbfb8aa3b, v26
	v_exp_f32_e32 v17, v17
	v_and_b32_e32 v35, 0xffff0000, v24
	v_lshlrev_b32_e32 v24, 16, v20
	v_and_b32_e32 v25, 0xffff0000, v20
	v_add_f32_e32 v17, 1.0, v17
	v_rcp_f32_e32 v30, v17
	v_mul_f32_e32 v17, 0xbfb8aa3b, v27
	v_exp_f32_e32 v17, v17
	v_pk_mul_f32 v[20:21], v[48:49], v[24:25]
	v_lshlrev_b32_e32 v24, 16, v16
	v_pk_fma_f32 v[20:21], v[28:29], v[34:35], v[20:21]
	v_add_f32_e32 v17, 1.0, v17
	v_and_b32_e32 v25, 0xffff0000, v16
	v_rcp_f32_e32 v31, v17
	v_pk_fma_f32 v[16:17], v[32:33], v[24:25], v[20:21]
	v_mul_f32_e32 v22, 0xbfb8aa3b, v18
	v_mul_f32_e32 v20, 0xbfb8aa3b, v16
	v_mul_f32_e32 v21, 0xbfb8aa3b, v17
	v_exp_f32_e32 v20, v20
	v_exp_f32_e32 v21, v21
	v_mul_f32_e32 v23, 0xbfb8aa3b, v19
	v_exp_f32_e32 v22, v22
	v_exp_f32_e32 v23, v23
	v_add_f32_e32 v20, 1.0, v20
	v_add_f32_e32 v21, 1.0, v21
	v_rcp_f32_e32 v20, v20
	v_rcp_f32_e32 v21, v21
	v_add_f32_e32 v22, 1.0, v22
	v_add_f32_e32 v23, 1.0, v23
	v_rcp_f32_e32 v22, v22
	v_rcp_f32_e32 v23, v23
	v_pk_mul_f32 v[16:17], v[16:17], v[20:21]
	v_pk_mul_f32 v[26:27], v[26:27], v[30:31]
	v_pk_mul_f32 v[20:21], v[16:17], v[16:17]
	v_pk_mul_f32 v[30:31], v[26:27], v[26:27]
	v_add_f32_e32 v20, v20, v21
	v_pk_mul_f32 v[18:19], v[18:19], v[22:23]
	v_add_f32_e32 v20, v20, v30
	v_pk_mul_f32 v[22:23], v[18:19], v[18:19]
	v_add_f32_e32 v20, v20, v31
	v_pk_mul_f32 v[36:37], v[36:37], v[38:39]
	v_add_f32_e32 v20, v20, v22
	v_pk_mul_f32 v[38:39], v[36:37], v[36:37]
	v_add_f32_e32 v20, v20, v23
	v_add_f32_e32 v20, v20, v38
	v_add_f32_e32 v20, v20, v39
	ds_bpermute_b32 v21, v140, v20
	v_lshlrev_b32_e32 v40, 16, v12
	v_and_b32_e32 v41, 0xffff0000, v12
	v_lshlrev_b32_e32 v12, 16, v13
	v_and_b32_e32 v13, 0xffff0000, v13
	s_waitcnt lgkmcnt(0)
	v_add_f32_e32 v20, v20, v21
	ds_bpermute_b32 v21, v141, v20
	s_waitcnt lgkmcnt(0)
	v_add_f32_e32 v20, v20, v21
	ds_bpermute_b32 v21, v142, v20
	s_waitcnt lgkmcnt(0)
	v_add_f32_e32 v20, v20, v21
	v_add_f32_e32 v20, 0x358637bd, v20
	v_rsq_f32_e32 v20, v20
	s_nop 0
	v_pk_mul_f32 v[16:17], v[16:17], v[20:21] op_sel_hi:[1,0]
	v_pk_mul_f32 v[22:23], v[26:27], v[20:21] op_sel_hi:[1,0]
	v_pk_mul_f32 v[18:19], v[18:19], v[20:21] op_sel_hi:[1,0]
	v_pk_mul_f32 v[20:21], v[36:37], v[20:21] op_sel_hi:[1,0]
	v_cvt_pk_bf16_f32 v18, v18, v19
	v_cvt_pk_bf16_f32 v19, v20, v21
	v_add_co_u32_e32 v20, vcc, s2, v134
	v_cvt_pk_bf16_f32 v16, v16, v17
	v_cvt_pk_bf16_f32 v17, v22, v23
	v_addc_co_u32_e32 v21, vcc, 0, v135, vcc
	global_store_dwordx4 v[20:21], v[16:19], off
	s_nop 1
	ds_read_b128 v[16:19], v162 offset:4112
	s_nop 0
	ds_read_b128 v[20:23], v162 offset:4096
	ds_read_b128 v[24:27], v162 offset:10256
	ds_read_b128 v[28:31], v162 offset:10240
	ds_read_b128 v[32:35], v162 offset:16400
	ds_read_b128 v[36:39], v162 offset:16384
	s_waitcnt lgkmcnt(0)
	v_pk_mul_f32 v[28:29], v[28:29], v[42:43]
	s_nop 0
	v_pk_fma_f32 v[20:21], v[20:21], v[40:41], v[28:29]
	v_lshlrev_b32_e32 v28, 16, v4
	v_and_b32_e32 v29, 0xffff0000, v4
	s_waitcnt lgkmcnt(0)
	v_pk_fma_f32 v[20:21], v[36:37], v[28:29], v[20:21]
	v_pk_mul_f32 v[8:9], v[30:31], v[8:9]
	v_mul_f32_e32 v4, 0xbfb8aa3b, v20
	v_exp_f32_e32 v4, v4
	v_pk_fma_f32 v[8:9], v[22:23], v[12:13], v[8:9]
	v_lshlrev_b32_e32 v12, 16, v10
	v_and_b32_e32 v13, 0xffff0000, v10
	v_add_f32_e32 v4, 1.0, v4
	v_rcp_f32_e32 v28, v4
	v_mul_f32_e32 v4, 0xbfb8aa3b, v21
	v_exp_f32_e32 v4, v4
	v_pk_mul_f32 v[12:13], v[24:25], v[12:13]
	v_lshlrev_b32_e32 v10, 16, v11
	v_and_b32_e32 v11, 0xffff0000, v11
	v_add_f32_e32 v4, 1.0, v4
	v_rcp_f32_e32 v29, v4
	v_lshlrev_b32_e32 v4, 16, v5
	v_and_b32_e32 v5, 0xffff0000, v5
	v_pk_fma_f32 v[4:5], v[38:39], v[4:5], v[8:9]
	v_pk_mul_f32 v[10:11], v[26:27], v[10:11]
	v_mul_f32_e32 v8, 0xbfb8aa3b, v4
	v_mul_f32_e32 v9, 0xbfb8aa3b, v5
	v_exp_f32_e32 v8, v8
	v_exp_f32_e32 v9, v9
	v_pk_mul_f32 v[20:21], v[20:21], v[28:29]
	v_add_f32_e32 v8, 1.0, v8
	v_add_f32_e32 v9, 1.0, v9
	v_rcp_f32_e32 v8, v8
	v_rcp_f32_e32 v9, v9
	s_nop 0
	v_pk_mul_f32 v[8:9], v[4:5], v[8:9]
	v_lshlrev_b32_e32 v4, 16, v14
	v_and_b32_e32 v5, 0xffff0000, v14
	v_pk_fma_f32 v[4:5], v[16:17], v[4:5], v[12:13]
	v_lshlrev_b32_e32 v12, 16, v6
	v_and_b32_e32 v13, 0xffff0000, v6
	v_pk_fma_f32 v[4:5], v[32:33], v[12:13], v[4:5]
	s_nop 0
	v_mul_f32_e32 v6, 0xbfb8aa3b, v4
	v_exp_f32_e32 v6, v6
	s_nop 0
	v_add_f32_e32 v6, 1.0, v6
	v_rcp_f32_e32 v12, v6
	v_mul_f32_e32 v6, 0xbfb8aa3b, v5
	v_exp_f32_e32 v6, v6
	s_nop 0
	v_add_f32_e32 v6, 1.0, v6
	v_rcp_f32_e32 v13, v6
	v_lshlrev_b32_e32 v6, 16, v7
	v_and_b32_e32 v7, 0xffff0000, v7
	v_pk_mul_f32 v[12:13], v[4:5], v[12:13]
	v_lshlrev_b32_e32 v4, 16, v15
	v_and_b32_e32 v5, 0xffff0000, v15
	v_pk_fma_f32 v[4:5], v[18:19], v[4:5], v[10:11]
	s_nop 0
	v_pk_fma_f32 v[4:5], v[34:35], v[6:7], v[4:5]
	s_nop 0
	v_mul_f32_e32 v6, 0xbfb8aa3b, v4
	v_mul_f32_e32 v7, 0xbfb8aa3b, v5
	v_exp_f32_e32 v6, v6
	v_exp_f32_e32 v7, v7
	v_add_f32_e32 v6, 1.0, v6
	v_add_f32_e32 v7, 1.0, v7
	v_rcp_f32_e32 v6, v6
	v_rcp_f32_e32 v7, v7
	s_nop 0
	v_pk_mul_f32 v[10:11], v[4:5], v[6:7]
	v_cvt_pk_bf16_f32 v5, v8, v9
	v_add_co_u32_e32 v8, vcc, 0x9530000, v134
	v_cvt_pk_bf16_f32 v4, v20, v21
	v_cvt_pk_bf16_f32 v6, v12, v13
	v_cvt_pk_bf16_f32 v7, v10, v11
	v_addc_co_u32_e32 v9, vcc, 0, v135, vcc
	global_store_dwordx4 v[8:9], v[4:7], off
	s_nop 1
